# group-A pre-epilogue barrier moved deeper into the epilogue (P8 after 7 of 16 stores, EpiRes phases after 3 of 8 chunks)
# baseline (speedup 1.0000x reference)
.LBB0_1211:
	s_or_b64 exec, exec, s[36:37]
	s_and_b64 vcc, exec, s[10:11]
	s_cbranch_vccz .Lepibar_P5a
	s_barrier
.Lepibar_P5a:
	v_lshlrev_b32_e32 v80, 16, v132
	s_waitcnt lgkmcnt(0)
	v_and_b32_e32 v81, 0xffff0000, v132
	v_lshlrev_b32_e32 v82, 16, v133
	v_and_b32_e32 v83, 0xffff0000, v133
	v_lshlrev_b32_e32 v84, 16, v134
	v_and_b32_e32 v85, 0xffff0000, v134
	v_lshlrev_b32_e32 v86, 16, v135
	v_and_b32_e32 v87, 0xffff0000, v135
	v_pk_add_f32 v[78:79], v[78:79], v[82:83]
	v_pk_add_f32 v[76:77], v[76:77], v[80:81]
	v_pk_add_f32 v[80:81], v[74:75], v[86:87]
	v_pk_add_f32 v[74:75], v[72:73], v[84:85]
	v_mul_f32_e32 v72, v77, v77
	v_mul_f32_e32 v73, v79, v79
	v_fmac_f32_e32 v72, v76, v76
	v_fmac_f32_e32 v73, v78, v78
	v_add_f32_e32 v72, v72, v73
	v_mul_f32_e32 v73, v75, v75
	v_mul_f32_e32 v82, v81, v81
	v_fmac_f32_e32 v73, v74, v74
	v_fmac_f32_e32 v82, v80, v80
	v_lshlrev_b32_e32 v88, 16, v128
	v_and_b32_e32 v89, 0xffff0000, v128
	v_lshlrev_b32_e32 v90, 16, v129
	v_and_b32_e32 v91, 0xffff0000, v129
	v_add_f32_e32 v73, v73, v82
	v_lshlrev_b32_e32 v94, 16, v131
	v_and_b32_e32 v95, 0xffff0000, v131
	v_add_f32_e32 v82, v72, v73
	v_cvt_pk_bf16_f32 v72, v76, v77
	v_cvt_pk_bf16_f32 v73, v78, v79
	v_lshl_add_u64 v[76:77], v[160:161], 0, s[34:35]
	v_pk_add_f32 v[70:71], v[70:71], v[90:91]
	v_pk_add_f32 v[68:69], v[68:69], v[88:89]
	v_lshlrev_b32_e32 v92, 16, v130
	v_and_b32_e32 v93, 0xffff0000, v130
	v_cvt_pk_bf16_f32 v74, v74, v75
	v_cvt_pk_bf16_f32 v75, v80, v81
	global_store_dwordx4 v[76:77], v[72:75], off
	v_pk_add_f32 v[64:65], v[64:65], v[92:93]
	s_add_u32 s30, s30, s23
	v_pk_add_f32 v[72:73], v[66:67], v[94:95]
	v_mul_f32_e32 v66, v69, v69
	v_mul_f32_e32 v67, v71, v71
	v_fmac_f32_e32 v66, v68, v68
	v_fmac_f32_e32 v67, v70, v70
	v_add_f32_e32 v66, v66, v67
	v_mul_f32_e32 v67, v65, v65
	v_mul_f32_e32 v74, v73, v73
	v_fmac_f32_e32 v67, v64, v64
	v_fmac_f32_e32 v74, v72, v72
	v_add_f32_e32 v67, v67, v74
	v_add_f32_e32 v66, v66, v67
	v_add_f32_e32 v74, v82, v66
	ds_bpermute_b32 v75, v112, v74
	v_cvt_pk_bf16_f32 v66, v68, v69
	v_cvt_pk_bf16_f32 v67, v70, v71
	v_cvt_pk_bf16_f32 v68, v64, v65
	s_addc_u32 s31, s31, s21
	s_waitcnt lgkmcnt(0)
	v_add_f32_e32 v64, v74, v75
	ds_bpermute_b32 v65, v113, v64
	s_lshl_b64 s[30:31], s[30:31], 10
	v_lshl_add_u64 v[70:71], v[160:161], 0, s[30:31]
	v_cvt_pk_bf16_f32 v69, v72, v73
	global_store_dwordx4 v[70:71], v[66:69], off
	s_and_saveexec_b64 s[30:31], s[2:3]
	s_cbranch_execz .LBB0_1213
	v_or_b32_e32 v66, 48, v172
	v_ashrrev_i32_e32 v67, 31, v66
	s_waitcnt lgkmcnt(0)
	v_add_f32_e32 v68, v64, v65
	s_lshl_b32 s34, s6, 2
	v_lshlrev_b64 v[64:65], 8, v[66:67]
	s_ashr_i32 s35, s34, 31
	v_lshl_add_u64 v[64:65], s[14:15], 0, v[64:65]
	v_lshl_add_u64 v[64:65], s[34:35], 2, v[64:65]
	s_lshl_b32 s8, s62, 2
	v_lshl_add_u64 v[64:65], v[64:65], 0, s[8:9]
	global_store_dword v[64:65], v68, off

.LBB0_1444:
	s_or_b64 exec, exec, s[28:29]
	s_and_b64 vcc, exec, s[8:9]
	s_cbranch_vccz .Lepibar_P7
	s_barrier
.Lepibar_P7:
	v_lshlrev_b32_e32 v80, 16, v132
	s_waitcnt lgkmcnt(0)
	v_and_b32_e32 v81, 0xffff0000, v132
	v_lshlrev_b32_e32 v82, 16, v133
	v_and_b32_e32 v83, 0xffff0000, v133
	v_lshlrev_b32_e32 v84, 16, v134
	v_and_b32_e32 v85, 0xffff0000, v134
	v_lshlrev_b32_e32 v86, 16, v135
	v_and_b32_e32 v87, 0xffff0000, v135
	v_pk_add_f32 v[78:79], v[78:79], v[82:83]
	v_pk_add_f32 v[76:77], v[76:77], v[80:81]
	v_pk_add_f32 v[80:81], v[74:75], v[86:87]
	v_pk_add_f32 v[74:75], v[72:73], v[84:85]
	v_mul_f32_e32 v72, v77, v77
	v_mul_f32_e32 v73, v79, v79
	v_fmac_f32_e32 v72, v76, v76
	v_fmac_f32_e32 v73, v78, v78
	v_add_f32_e32 v72, v72, v73
	v_mul_f32_e32 v73, v75, v75
	v_mul_f32_e32 v82, v81, v81
	v_fmac_f32_e32 v73, v74, v74
	v_fmac_f32_e32 v82, v80, v80
	v_lshlrev_b32_e32 v88, 16, v128
	v_and_b32_e32 v89, 0xffff0000, v128
	v_lshlrev_b32_e32 v90, 16, v129
	v_and_b32_e32 v91, 0xffff0000, v129
	v_add_f32_e32 v73, v73, v82
	v_lshlrev_b32_e32 v94, 16, v131
	v_and_b32_e32 v95, 0xffff0000, v131
	v_add_f32_e32 v82, v72, v73
	v_cvt_pk_bf16_f32 v72, v76, v77
	v_cvt_pk_bf16_f32 v73, v78, v79
	v_pk_add_f32 v[70:71], v[70:71], v[90:91]
	v_pk_add_f32 v[68:69], v[68:69], v[88:89]
	v_lshlrev_b32_e32 v92, 16, v130
	v_and_b32_e32 v93, 0xffff0000, v130
	v_cvt_pk_bf16_f32 v74, v74, v75
	v_cvt_pk_bf16_f32 v75, v80, v81
	global_store_dwordx4 v[172:173], v[72:75], off
	v_pk_add_f32 v[64:65], v[64:65], v[92:93]
	s_add_u32 s26, s26, s17
	v_pk_add_f32 v[72:73], v[66:67], v[94:95]
	v_mul_f32_e32 v66, v69, v69
	v_mul_f32_e32 v67, v71, v71
	v_fmac_f32_e32 v66, v68, v68
	v_fmac_f32_e32 v67, v70, v70
	v_add_f32_e32 v66, v66, v67
	v_mul_f32_e32 v67, v65, v65
	v_mul_f32_e32 v74, v73, v73
	v_fmac_f32_e32 v67, v64, v64
	v_fmac_f32_e32 v74, v72, v72
	v_add_f32_e32 v67, v67, v74
	v_add_f32_e32 v66, v66, v67
	v_add_f32_e32 v74, v82, v66
	ds_bpermute_b32 v75, v112, v74
	v_cvt_pk_bf16_f32 v66, v68, v69
	v_cvt_pk_bf16_f32 v67, v70, v71
	v_cvt_pk_bf16_f32 v68, v64, v65
	s_addc_u32 s27, s27, s1
	s_waitcnt lgkmcnt(0)
	v_add_f32_e32 v64, v74, v75
	ds_bpermute_b32 v65, v113, v64
	s_lshl_b64 s[26:27], s[26:27], 10
	v_lshl_add_u64 v[70:71], v[160:161], 0, s[26:27]
	v_cvt_pk_bf16_f32 v69, v72, v73
	global_store_dwordx4 v[70:71], v[66:69], off
	s_and_saveexec_b64 s[26:27], s[2:3]
	s_cbranch_execz .LBB0_1446
	v_or_b32_e32 v66, 48, v170
	v_ashrrev_i32_e32 v67, 31, v66
	s_waitcnt lgkmcnt(0)
	v_add_f32_e32 v68, v64, v65
	s_lshl_b32 s28, s0, 2
	v_lshlrev_b64 v[64:65], 8, v[66:67]
	s_ashr_i32 s29, s28, 31
	v_lshl_add_u64 v[64:65], s[12:13], 0, v[64:65]
	v_lshl_add_u64 v[64:65], s[28:29], 2, v[64:65]
	s_lshl_b32 s6, s44, 2
	v_lshl_add_u64 v[64:65], v[64:65], 0, s[6:7]
	global_store_dword v[64:65], v68, off

.LBB0_1550:
	s_lshl_b32 s11, s18, 4
	s_and_b32 s11, s11, 0x1f0
	s_or_b32 s22, s11, s43
	s_lshl_b32 s11, s49, 3
	s_or_b32 s20, s11, s40
	s_ashr_i32 s21, s20, 31
	s_cmp_lt_i32 s18, 32
	s_cselect_b32 s11, s47, 0x30100000
	s_add_u32 s11, s0, s11
	s_addc_u32 s13, s1, 0
	s_lshl_b32 s18, s22, 9
	s_add_u32 s22, s18, s20
	s_addc_u32 s23, 0, s21
	s_lshl_b64 s[22:23], s[22:23], 10
	v_pk_mul_f32 v[120:121], v[120:121], v[164:165] op_sel_hi:[1,0]
	s_add_u32 s22, s11, s22
	v_pk_mul_f32 v[124:125], v[124:125], v[164:165] op_sel_hi:[1,0]
	v_pk_mul_f32 v[122:123], v[122:123], v[164:165] op_sel_hi:[1,0]
	v_max_f32_e32 v120, 0, v120
	s_addc_u32 s23, s13, s23
	v_pk_mul_f32 v[126:127], v[126:127], v[164:165] op_sel_hi:[1,0]
	v_mul_f32_e32 v129, v120, v120
	v_max_f32_e32 v120, 0, v125
	v_max_f32_e32 v121, 0, v121
	v_max_f32_e32 v122, 0, v122
	v_lshl_add_u64 v[172:173], s[22:23], 0, v[140:141]
	v_mov_b32_e32 v153, v141
	v_max_f32_e32 v124, 0, v124
	v_mul_f32_e32 v120, v120, v120
	v_mul_f32_e32 v125, v121, v121
	v_max_f32_e32 v121, 0, v126
	v_mul_f32_e32 v126, v122, v122
	v_max_f32_e32 v122, 0, v127
	v_max_f32_e32 v123, 0, v123
	v_pk_mul_f32 v[112:113], v[112:113], v[164:165] op_sel_hi:[1,0]
	v_lshl_add_u64 v[172:173], v[172:173], 0, v[152:153]
	v_mul_f32_e32 v124, v124, v124
	v_mul_f32_e32 v121, v121, v121
	v_mul_f32_e32 v122, v122, v122
	v_mul_f32_e32 v123, v123, v123
	v_cvt_pk_bf16_f32 v120, v124, v120
	v_pk_mul_f32 v[116:117], v[116:117], v[164:165] op_sel_hi:[1,0]
	v_pk_mul_f32 v[114:115], v[114:115], v[164:165] op_sel_hi:[1,0]
	v_max_f32_e32 v112, 0, v112
	s_or_b32 s22, s18, 0x200
	v_cvt_pk_bf16_f32 v121, v121, v122
	v_cvt_pk_bf16_f32 v122, v129, v125
	v_cvt_pk_bf16_f32 v123, v126, v123
	global_store_dwordx4 v[172:173], v[120:123], off
	v_pk_mul_f32 v[118:119], v[118:119], v[164:165] op_sel_hi:[1,0]
	v_max_f32_e32 v116, 0, v116
	v_mul_f32_e32 v120, v112, v112
	v_max_f32_e32 v112, 0, v117
	v_max_f32_e32 v113, 0, v113
	v_max_f32_e32 v114, 0, v114
	s_add_u32 s22, s22, s20
	v_mul_f32_e32 v116, v116, v116
	v_mul_f32_e32 v112, v112, v112
	v_mul_f32_e32 v117, v113, v113
	v_max_f32_e32 v113, 0, v118
	v_mul_f32_e32 v118, v114, v114
	v_max_f32_e32 v114, 0, v119
	s_addc_u32 s23, 0, s21
	v_mul_f32_e32 v113, v113, v113
	v_mul_f32_e32 v114, v114, v114
	v_max_f32_e32 v115, 0, v115
	v_cvt_pk_bf16_f32 v112, v116, v112
	v_add_co_u32_e32 v116, vcc, s48, v172
	s_lshl_b64 s[22:23], s[22:23], 10
	v_pk_mul_f32 v[104:105], v[104:105], v[162:163] op_sel_hi:[1,0]
	v_mul_f32_e32 v115, v115, v115
	v_cvt_pk_bf16_f32 v113, v113, v114
	v_cvt_pk_bf16_f32 v114, v120, v117
	v_addc_co_u32_e32 v117, vcc, 0, v173, vcc
	s_add_u32 s22, s11, s22
	v_pk_mul_f32 v[108:109], v[108:109], v[162:163] op_sel_hi:[1,0]
	v_pk_mul_f32 v[106:107], v[106:107], v[162:163] op_sel_hi:[1,0]
	v_max_f32_e32 v104, 0, v104
	v_cvt_pk_bf16_f32 v115, v118, v115
	global_store_dwordx4 v[116:117], v[112:115], off
	s_addc_u32 s23, s13, s23
	v_pk_mul_f32 v[110:111], v[110:111], v[162:163] op_sel_hi:[1,0]
	v_mul_f32_e32 v114, v104, v104
	v_max_f32_e32 v104, 0, v109
	v_max_f32_e32 v105, 0, v105
	v_max_f32_e32 v106, 0, v106
	v_lshl_add_u64 v[112:113], s[22:23], 0, v[140:141]
	v_max_f32_e32 v108, 0, v108
	v_mul_f32_e32 v104, v104, v104
	v_mul_f32_e32 v109, v105, v105
	v_max_f32_e32 v105, 0, v110
	v_mul_f32_e32 v110, v106, v106
	v_max_f32_e32 v106, 0, v111
	v_max_f32_e32 v107, 0, v107
	v_pk_mul_f32 v[96:97], v[96:97], v[162:163] op_sel_hi:[1,0]
	v_lshl_add_u64 v[112:113], v[112:113], 0, v[152:153]
	v_mul_f32_e32 v108, v108, v108
	v_mul_f32_e32 v105, v105, v105
	v_mul_f32_e32 v106, v106, v106
	v_mul_f32_e32 v107, v107, v107
	v_cvt_pk_bf16_f32 v104, v108, v104
	v_pk_mul_f32 v[100:101], v[100:101], v[162:163] op_sel_hi:[1,0]
	v_pk_mul_f32 v[98:99], v[98:99], v[162:163] op_sel_hi:[1,0]
	v_max_f32_e32 v96, 0, v96
	s_or_b32 s22, s18, 0x400
	v_cvt_pk_bf16_f32 v105, v105, v106
	v_cvt_pk_bf16_f32 v106, v114, v109
	v_cvt_pk_bf16_f32 v107, v110, v107
	global_store_dwordx4 v[112:113], v[104:107], off
	v_pk_mul_f32 v[102:103], v[102:103], v[162:163] op_sel_hi:[1,0]
	v_max_f32_e32 v100, 0, v100
	v_mul_f32_e32 v104, v96, v96
	v_max_f32_e32 v96, 0, v101
	v_max_f32_e32 v97, 0, v97
	v_max_f32_e32 v98, 0, v98
	s_add_u32 s22, s22, s20
	v_mul_f32_e32 v100, v100, v100
	v_mul_f32_e32 v96, v96, v96
	v_mul_f32_e32 v101, v97, v97
	v_max_f32_e32 v97, 0, v102
	v_mul_f32_e32 v102, v98, v98
	v_max_f32_e32 v98, 0, v103
	s_addc_u32 s23, 0, s21
	v_mul_f32_e32 v97, v97, v97
	v_mul_f32_e32 v98, v98, v98
	v_max_f32_e32 v99, 0, v99
	v_cvt_pk_bf16_f32 v96, v100, v96
	v_add_co_u32_e32 v100, vcc, s48, v112
	s_lshl_b64 s[22:23], s[22:23], 10
	v_pk_mul_f32 v[88:89], v[88:89], v[160:161] op_sel_hi:[1,0]
	v_mul_f32_e32 v99, v99, v99
	v_cvt_pk_bf16_f32 v97, v97, v98
	v_cvt_pk_bf16_f32 v98, v104, v101
	v_addc_co_u32_e32 v101, vcc, 0, v113, vcc
	s_add_u32 s22, s11, s22
	v_pk_mul_f32 v[92:93], v[92:93], v[160:161] op_sel_hi:[1,0]
	v_pk_mul_f32 v[90:91], v[90:91], v[160:161] op_sel_hi:[1,0]
	v_max_f32_e32 v88, 0, v88
	v_cvt_pk_bf16_f32 v99, v102, v99
	global_store_dwordx4 v[100:101], v[96:99], off
	s_addc_u32 s23, s13, s23
	v_pk_mul_f32 v[94:95], v[94:95], v[160:161] op_sel_hi:[1,0]
	v_mul_f32_e32 v98, v88, v88
	v_max_f32_e32 v88, 0, v93
	v_max_f32_e32 v89, 0, v89
	v_max_f32_e32 v90, 0, v90
	v_lshl_add_u64 v[96:97], s[22:23], 0, v[140:141]
	v_max_f32_e32 v92, 0, v92
	v_mul_f32_e32 v88, v88, v88
	v_mul_f32_e32 v93, v89, v89
	v_max_f32_e32 v89, 0, v94
	v_mul_f32_e32 v94, v90, v90
	v_max_f32_e32 v90, 0, v95
	v_max_f32_e32 v91, 0, v91
	v_pk_mul_f32 v[80:81], v[80:81], v[160:161] op_sel_hi:[1,0]
	v_lshl_add_u64 v[96:97], v[96:97], 0, v[152:153]
	v_mul_f32_e32 v92, v92, v92
	v_mul_f32_e32 v89, v89, v89
	v_mul_f32_e32 v90, v90, v90
	v_mul_f32_e32 v91, v91, v91
	v_cvt_pk_bf16_f32 v88, v92, v88
	v_pk_mul_f32 v[84:85], v[84:85], v[160:161] op_sel_hi:[1,0]
	v_pk_mul_f32 v[82:83], v[82:83], v[160:161] op_sel_hi:[1,0]
	v_max_f32_e32 v80, 0, v80
	s_or_b32 s22, s18, 0x600
	v_cvt_pk_bf16_f32 v89, v89, v90
	v_cvt_pk_bf16_f32 v90, v98, v93
	v_cvt_pk_bf16_f32 v91, v94, v91
	global_store_dwordx4 v[96:97], v[88:91], off
	v_pk_mul_f32 v[86:87], v[86:87], v[160:161] op_sel_hi:[1,0]
	v_max_f32_e32 v84, 0, v84
	v_mul_f32_e32 v88, v80, v80
	v_max_f32_e32 v80, 0, v85
	v_max_f32_e32 v81, 0, v81
	v_max_f32_e32 v82, 0, v82
	s_add_u32 s22, s22, s20
	v_mul_f32_e32 v84, v84, v84
	v_mul_f32_e32 v80, v80, v80
	v_mul_f32_e32 v85, v81, v81
	v_max_f32_e32 v81, 0, v86
	v_mul_f32_e32 v86, v82, v82
	v_max_f32_e32 v82, 0, v87
	s_addc_u32 s23, 0, s21
	v_mul_f32_e32 v81, v81, v81
	v_mul_f32_e32 v82, v82, v82
	v_max_f32_e32 v83, 0, v83
	v_cvt_pk_bf16_f32 v80, v84, v80
	v_add_co_u32_e32 v84, vcc, s48, v96
	s_lshl_b64 s[22:23], s[22:23], 10
	v_pk_mul_f32 v[72:73], v[72:73], v[158:159] op_sel_hi:[1,0]
	v_mul_f32_e32 v83, v83, v83
	v_cvt_pk_bf16_f32 v81, v81, v82
	v_cvt_pk_bf16_f32 v82, v88, v85
	v_addc_co_u32_e32 v85, vcc, 0, v97, vcc
	s_add_u32 s22, s11, s22
	v_pk_mul_f32 v[76:77], v[76:77], v[158:159] op_sel_hi:[1,0]
	v_pk_mul_f32 v[74:75], v[74:75], v[158:159] op_sel_hi:[1,0]
	v_max_f32_e32 v72, 0, v72
	v_cvt_pk_bf16_f32 v83, v86, v83
	global_store_dwordx4 v[84:85], v[80:83], off
	s_addc_u32 s23, s13, s23
	v_pk_mul_f32 v[78:79], v[78:79], v[158:159] op_sel_hi:[1,0]
	v_mul_f32_e32 v82, v72, v72
	v_max_f32_e32 v72, 0, v77
	v_max_f32_e32 v73, 0, v73
	v_max_f32_e32 v74, 0, v74
	v_lshl_add_u64 v[80:81], s[22:23], 0, v[140:141]
	v_max_f32_e32 v76, 0, v76
	v_mul_f32_e32 v72, v72, v72
	v_mul_f32_e32 v77, v73, v73
	v_max_f32_e32 v73, 0, v78
	v_mul_f32_e32 v78, v74, v74
	v_max_f32_e32 v74, 0, v79
	v_max_f32_e32 v75, 0, v75
	v_pk_mul_f32 v[64:65], v[64:65], v[158:159] op_sel_hi:[1,0]
	v_lshl_add_u64 v[80:81], v[80:81], 0, v[152:153]
	v_mul_f32_e32 v76, v76, v76
	v_mul_f32_e32 v73, v73, v73
	v_mul_f32_e32 v74, v74, v74
	v_mul_f32_e32 v75, v75, v75
	v_cvt_pk_bf16_f32 v72, v76, v72
	v_pk_mul_f32 v[68:69], v[68:69], v[158:159] op_sel_hi:[1,0]
	v_pk_mul_f32 v[66:67], v[66:67], v[158:159] op_sel_hi:[1,0]
	v_max_f32_e32 v64, 0, v64
	s_or_b32 s22, s18, 0x1000
	v_cvt_pk_bf16_f32 v73, v73, v74
	v_cvt_pk_bf16_f32 v74, v82, v77
	v_cvt_pk_bf16_f32 v75, v78, v75
	global_store_dwordx4 v[80:81], v[72:75], off
	s_and_b64 vcc, exec, s[4:5]
	s_cbranch_vccz .Lepibar_P8
	s_barrier
.Lepibar_P8:
	v_pk_mul_f32 v[70:71], v[70:71], v[158:159] op_sel_hi:[1,0]
	v_max_f32_e32 v68, 0, v68
	v_mul_f32_e32 v72, v64, v64
	v_max_f32_e32 v64, 0, v69
	v_max_f32_e32 v65, 0, v65
	v_max_f32_e32 v66, 0, v66
	s_add_u32 s22, s22, s20
	v_mul_f32_e32 v68, v68, v68
	v_mul_f32_e32 v64, v64, v64
	v_mul_f32_e32 v69, v65, v65
	v_max_f32_e32 v65, 0, v70
	v_mul_f32_e32 v70, v66, v66
	v_max_f32_e32 v66, 0, v71
	s_addc_u32 s23, 0, s21
	v_mul_f32_e32 v65, v65, v65
	v_mul_f32_e32 v66, v66, v66
	v_max_f32_e32 v67, 0, v67
	v_cvt_pk_bf16_f32 v64, v68, v64
	v_add_co_u32_e32 v68, vcc, s48, v80
	s_lshl_b64 s[22:23], s[22:23], 10
	v_pk_mul_f32 v[56:57], v[56:57], v[156:157] op_sel_hi:[1,0]
	v_mul_f32_e32 v67, v67, v67
	v_cvt_pk_bf16_f32 v65, v65, v66
	v_cvt_pk_bf16_f32 v66, v72, v69
	v_addc_co_u32_e32 v69, vcc, 0, v81, vcc
	s_add_u32 s22, s11, s22
	v_pk_mul_f32 v[60:61], v[60:61], v[156:157] op_sel_hi:[1,0]
	v_pk_mul_f32 v[58:59], v[58:59], v[156:157] op_sel_hi:[1,0]
	v_max_f32_e32 v56, 0, v56
	v_cvt_pk_bf16_f32 v67, v70, v67
	global_store_dwordx4 v[68:69], v[64:67], off
	s_addc_u32 s23, s13, s23
	v_pk_mul_f32 v[62:63], v[62:63], v[156:157] op_sel_hi:[1,0]
	v_mul_f32_e32 v66, v56, v56
	v_max_f32_e32 v56, 0, v61
	v_max_f32_e32 v57, 0, v57
	v_max_f32_e32 v58, 0, v58
	v_lshl_add_u64 v[64:65], s[22:23], 0, v[140:141]
	v_max_f32_e32 v60, 0, v60
	v_mul_f32_e32 v56, v56, v56
	v_mul_f32_e32 v61, v57, v57
	v_max_f32_e32 v57, 0, v62
	v_mul_f32_e32 v62, v58, v58
	v_max_f32_e32 v58, 0, v63
	v_max_f32_e32 v59, 0, v59
	v_pk_mul_f32 v[48:49], v[48:49], v[156:157] op_sel_hi:[1,0]
	v_lshl_add_u64 v[64:65], v[64:65], 0, v[152:153]
	v_mul_f32_e32 v60, v60, v60
	v_mul_f32_e32 v57, v57, v57
	v_mul_f32_e32 v58, v58, v58
	v_mul_f32_e32 v59, v59, v59
	v_cvt_pk_bf16_f32 v56, v60, v56
	v_pk_mul_f32 v[52:53], v[52:53], v[156:157] op_sel_hi:[1,0]
	v_pk_mul_f32 v[50:51], v[50:51], v[156:157] op_sel_hi:[1,0]
	v_max_f32_e32 v48, 0, v48
	s_or_b32 s22, s18, 0x1200
	v_cvt_pk_bf16_f32 v57, v57, v58
	v_cvt_pk_bf16_f32 v58, v66, v61
	v_cvt_pk_bf16_f32 v59, v62, v59
	global_store_dwordx4 v[64:65], v[56:59], off
	v_pk_mul_f32 v[54:55], v[54:55], v[156:157] op_sel_hi:[1,0]
	v_max_f32_e32 v52, 0, v52
	v_mul_f32_e32 v56, v48, v48
	v_max_f32_e32 v48, 0, v53
	v_max_f32_e32 v49, 0, v49
	v_max_f32_e32 v50, 0, v50
	s_add_u32 s22, s22, s20
	v_mul_f32_e32 v52, v52, v52
	v_mul_f32_e32 v48, v48, v48
	v_mul_f32_e32 v53, v49, v49
	v_max_f32_e32 v49, 0, v54
	v_mul_f32_e32 v54, v50, v50
	v_max_f32_e32 v50, 0, v55
	s_addc_u32 s23, 0, s21
	v_mul_f32_e32 v49, v49, v49
	v_mul_f32_e32 v50, v50, v50
	v_max_f32_e32 v51, 0, v51
	v_cvt_pk_bf16_f32 v48, v52, v48
	v_add_co_u32_e32 v52, vcc, s48, v64
	s_lshl_b64 s[22:23], s[22:23], 10
	v_pk_mul_f32 v[40:41], v[40:41], v[154:155] op_sel_hi:[1,0]
	v_mul_f32_e32 v51, v51, v51
	v_cvt_pk_bf16_f32 v49, v49, v50
	v_cvt_pk_bf16_f32 v50, v56, v53
	v_addc_co_u32_e32 v53, vcc, 0, v65, vcc
	s_add_u32 s22, s11, s22
	v_pk_mul_f32 v[44:45], v[44:45], v[154:155] op_sel_hi:[1,0]
	v_pk_mul_f32 v[42:43], v[42:43], v[154:155] op_sel_hi:[1,0]
	v_max_f32_e32 v40, 0, v40
	v_cvt_pk_bf16_f32 v51, v54, v51
	global_store_dwordx4 v[52:53], v[48:51], off
	s_addc_u32 s23, s13, s23
	v_pk_mul_f32 v[46:47], v[46:47], v[154:155] op_sel_hi:[1,0]
	v_mul_f32_e32 v50, v40, v40
	v_max_f32_e32 v40, 0, v45
	v_max_f32_e32 v41, 0, v41
	v_max_f32_e32 v42, 0, v42
	v_lshl_add_u64 v[48:49], s[22:23], 0, v[140:141]
	v_max_f32_e32 v44, 0, v44
	v_mul_f32_e32 v40, v40, v40
	v_mul_f32_e32 v45, v41, v41
	v_max_f32_e32 v41, 0, v46
	v_mul_f32_e32 v46, v42, v42
	v_max_f32_e32 v42, 0, v47
	v_max_f32_e32 v43, 0, v43
	v_pk_mul_f32 v[32:33], v[32:33], v[154:155] op_sel_hi:[1,0]
	v_lshl_add_u64 v[48:49], v[48:49], 0, v[152:153]
	v_mul_f32_e32 v44, v44, v44
	v_mul_f32_e32 v41, v41, v41
	v_mul_f32_e32 v42, v42, v42
	v_mul_f32_e32 v43, v43, v43
	v_cvt_pk_bf16_f32 v40, v44, v40
	v_pk_mul_f32 v[36:37], v[36:37], v[154:155] op_sel_hi:[1,0]
	v_pk_mul_f32 v[34:35], v[34:35], v[154:155] op_sel_hi:[1,0]
	v_max_f32_e32 v32, 0, v32
	s_or_b32 s22, s18, 0x1400
	v_cvt_pk_bf16_f32 v41, v41, v42
	v_cvt_pk_bf16_f32 v42, v50, v45
	v_cvt_pk_bf16_f32 v43, v46, v43
	global_store_dwordx4 v[48:49], v[40:43], off
	v_pk_mul_f32 v[38:39], v[38:39], v[154:155] op_sel_hi:[1,0]
	v_max_f32_e32 v36, 0, v36
	v_mul_f32_e32 v40, v32, v32
	v_max_f32_e32 v32, 0, v37
	v_max_f32_e32 v33, 0, v33
	v_max_f32_e32 v34, 0, v34
	s_add_u32 s22, s22, s20
	v_mul_f32_e32 v36, v36, v36
	v_mul_f32_e32 v32, v32, v32
	v_mul_f32_e32 v37, v33, v33
	v_max_f32_e32 v33, 0, v38
	v_mul_f32_e32 v38, v34, v34
	v_max_f32_e32 v34, 0, v39
	s_addc_u32 s23, 0, s21
	v_mul_f32_e32 v33, v33, v33
	v_mul_f32_e32 v34, v34, v34
	v_max_f32_e32 v35, 0, v35
	v_cvt_pk_bf16_f32 v32, v36, v32
	v_add_co_u32_e32 v36, vcc, s48, v48
	s_lshl_b64 s[22:23], s[22:23], 10
	v_pk_mul_f32 v[24:25], v[24:25], v[130:131] op_sel_hi:[1,0]
	v_mul_f32_e32 v35, v35, v35
	v_cvt_pk_bf16_f32 v33, v33, v34
	v_cvt_pk_bf16_f32 v34, v40, v37
	v_addc_co_u32_e32 v37, vcc, 0, v49, vcc
	s_add_u32 s22, s11, s22
	v_pk_mul_f32 v[28:29], v[28:29], v[130:131] op_sel_hi:[1,0]
	v_pk_mul_f32 v[26:27], v[26:27], v[130:131] op_sel_hi:[1,0]
	v_max_f32_e32 v24, 0, v24
	v_cvt_pk_bf16_f32 v35, v38, v35
	global_store_dwordx4 v[36:37], v[32:35], off
	s_addc_u32 s23, s13, s23
	v_pk_mul_f32 v[30:31], v[30:31], v[130:131] op_sel_hi:[1,0]
	v_mul_f32_e32 v34, v24, v24
	v_max_f32_e32 v24, 0, v29
	v_max_f32_e32 v25, 0, v25
	v_max_f32_e32 v26, 0, v26
	v_lshl_add_u64 v[32:33], s[22:23], 0, v[140:141]
	v_max_f32_e32 v28, 0, v28
	v_mul_f32_e32 v24, v24, v24
	v_mul_f32_e32 v29, v25, v25
	v_max_f32_e32 v25, 0, v30
	v_mul_f32_e32 v30, v26, v26
	v_max_f32_e32 v26, 0, v31
	v_max_f32_e32 v27, 0, v27
	v_pk_mul_f32 v[16:17], v[16:17], v[130:131] op_sel_hi:[1,0]
	v_lshl_add_u64 v[32:33], v[32:33], 0, v[152:153]
	v_mul_f32_e32 v28, v28, v28
	v_mul_f32_e32 v25, v25, v25
	v_mul_f32_e32 v26, v26, v26
	v_mul_f32_e32 v27, v27, v27
	v_cvt_pk_bf16_f32 v24, v28, v24
	v_pk_mul_f32 v[20:21], v[20:21], v[130:131] op_sel_hi:[1,0]
	v_pk_mul_f32 v[18:19], v[18:19], v[130:131] op_sel_hi:[1,0]
	v_max_f32_e32 v16, 0, v16
	s_or_b32 s18, s18, 0x1600
	v_cvt_pk_bf16_f32 v25, v25, v26
	v_cvt_pk_bf16_f32 v26, v34, v29
	v_cvt_pk_bf16_f32 v27, v30, v27
	global_store_dwordx4 v[32:33], v[24:27], off
	v_pk_mul_f32 v[22:23], v[22:23], v[130:131] op_sel_hi:[1,0]
	v_max_f32_e32 v20, 0, v20
	v_mul_f32_e32 v24, v16, v16
	v_max_f32_e32 v16, 0, v21
	v_max_f32_e32 v17, 0, v17
	v_max_f32_e32 v18, 0, v18
	s_add_u32 s20, s18, s20
	v_mul_f32_e32 v20, v20, v20
	v_mul_f32_e32 v16, v16, v16
	v_mul_f32_e32 v21, v17, v17
	v_max_f32_e32 v17, 0, v22
	v_mul_f32_e32 v22, v18, v18
	v_max_f32_e32 v18, 0, v23
	s_addc_u32 s21, 0, s21
	v_mul_f32_e32 v17, v17, v17
	v_mul_f32_e32 v18, v18, v18
	v_max_f32_e32 v19, 0, v19
	v_cvt_pk_bf16_f32 v16, v20, v16
	v_add_co_u32_e32 v20, vcc, s48, v32
	s_lshl_b64 s[20:21], s[20:21], 10
	v_pk_mul_f32 v[8:9], v[8:9], v[128:129] op_sel_hi:[1,0]
	v_mul_f32_e32 v19, v19, v19
	v_cvt_pk_bf16_f32 v17, v17, v18
	v_cvt_pk_bf16_f32 v18, v24, v21
	v_addc_co_u32_e32 v21, vcc, 0, v33, vcc
	s_add_u32 s20, s11, s20
	v_pk_mul_f32 v[12:13], v[12:13], v[128:129] op_sel_hi:[1,0]
	v_pk_mul_f32 v[10:11], v[10:11], v[128:129] op_sel_hi:[1,0]
	v_max_f32_e32 v8, 0, v8
	v_cvt_pk_bf16_f32 v19, v22, v19
	global_store_dwordx4 v[20:21], v[16:19], off
	s_addc_u32 s21, s13, s21
	v_pk_mul_f32 v[14:15], v[14:15], v[128:129] op_sel_hi:[1,0]
	v_mul_f32_e32 v18, v8, v8
	v_max_f32_e32 v8, 0, v13
	v_max_f32_e32 v9, 0, v9
	v_max_f32_e32 v10, 0, v10
	v_lshl_add_u64 v[16:17], s[20:21], 0, v[140:141]
	v_max_f32_e32 v12, 0, v12
	v_mul_f32_e32 v8, v8, v8
	v_mul_f32_e32 v13, v9, v9
	v_max_f32_e32 v9, 0, v14
	v_mul_f32_e32 v14, v10, v10
	v_max_f32_e32 v10, 0, v15
	v_max_f32_e32 v11, 0, v11
	v_pk_mul_f32 v[0:1], v[0:1], v[128:129] op_sel_hi:[1,0]
	v_lshl_add_u64 v[16:17], v[16:17], 0, v[152:153]
	v_mul_f32_e32 v12, v12, v12
	v_mul_f32_e32 v9, v9, v9
	v_mul_f32_e32 v10, v10, v10
	v_mul_f32_e32 v11, v11, v11
	v_cvt_pk_bf16_f32 v8, v12, v8
	v_pk_mul_f32 v[4:5], v[4:5], v[128:129] op_sel_hi:[1,0]
	v_pk_mul_f32 v[2:3], v[2:3], v[128:129] op_sel_hi:[1,0]
	v_max_f32_e32 v0, 0, v0
	v_cvt_pk_bf16_f32 v9, v9, v10
	v_cvt_pk_bf16_f32 v10, v18, v13
	v_cvt_pk_bf16_f32 v11, v14, v11
	global_store_dwordx4 v[16:17], v[8:11], off
	v_pk_mul_f32 v[6:7], v[6:7], v[128:129] op_sel_hi:[1,0]
	v_max_f32_e32 v4, 0, v4
	v_mul_f32_e32 v8, v0, v0
	v_max_f32_e32 v0, 0, v5
	v_max_f32_e32 v1, 0, v1
	v_max_f32_e32 v2, 0, v2
	v_mul_f32_e32 v4, v4, v4
	v_mul_f32_e32 v0, v0, v0
	v_mul_f32_e32 v5, v1, v1
	v_max_f32_e32 v1, 0, v6
	v_mul_f32_e32 v6, v2, v2
	v_max_f32_e32 v2, 0, v7
	v_mul_f32_e32 v1, v1, v1
	v_mul_f32_e32 v2, v2, v2
	v_cvt_pk_bf16_f32 v0, v4, v0
	v_add_co_u32_e32 v4, vcc, 0x1000, v16
	v_max_f32_e32 v3, 0, v3
	v_cvt_pk_bf16_f32 v1, v1, v2
	v_cvt_pk_bf16_f32 v2, v8, v5
	s_nop 0
	v_addc_co_u32_e32 v5, vcc, 0, v17, vcc
	v_mul_f32_e32 v3, v3, v3
	s_andn2_b64 vcc, exec, s[2:3]
	s_mov_b64 s[2:3], -1
	v_cvt_pk_bf16_f32 v3, v6, v3
	global_store_dwordx4 v[4:5], v[0:3], off
	s_cbranch_vccnz .LBB0_1535
	s_andn2_b64 vcc, exec, s[6:7]
	s_cbranch_vccnz .LBB0_1534
	s_barrier
	s_branch .LBB0_1534

.Lepibar_P9:
	v_lshlrev_b32_e32 v82, 16, v132
	v_and_b32_e32 v83, 0xffff0000, v132
	v_lshlrev_b32_e32 v84, 16, v133
	v_and_b32_e32 v85, 0xffff0000, v133
	v_lshlrev_b32_e32 v86, 16, v134
	v_and_b32_e32 v87, 0xffff0000, v134
	v_lshlrev_b32_e32 v88, 16, v135
	v_and_b32_e32 v89, 0xffff0000, v135
	v_pk_add_f32 v[78:79], v[78:79], v[84:85]
	v_pk_add_f32 v[76:77], v[76:77], v[82:83]
	v_pk_add_f32 v[82:83], v[74:75], v[88:89]
	v_pk_add_f32 v[74:75], v[72:73], v[86:87]
	v_mul_f32_e32 v72, v77, v77
	v_mul_f32_e32 v73, v79, v79
	v_fmac_f32_e32 v72, v76, v76
	v_fmac_f32_e32 v73, v78, v78
	v_add_f32_e32 v72, v72, v73
	v_mul_f32_e32 v73, v75, v75
	v_mul_f32_e32 v84, v83, v83
	v_lshlrev_b32_e32 v90, 16, v128
	v_and_b32_e32 v91, 0xffff0000, v128
	v_lshlrev_b32_e32 v92, 16, v129
	v_and_b32_e32 v93, 0xffff0000, v129
	v_fmac_f32_e32 v73, v74, v74
	v_fmac_f32_e32 v84, v82, v82
	v_lshlrev_b32_e32 v94, 16, v130
	v_and_b32_e32 v95, 0xffff0000, v130
	v_add_f32_e32 v73, v73, v84
	v_pk_add_f32 v[70:71], v[70:71], v[92:93]
	v_pk_add_f32 v[68:69], v[68:69], v[90:91]
	v_lshlrev_b32_e32 v96, 16, v131
	v_and_b32_e32 v97, 0xffff0000, v131
	v_add_f32_e32 v84, v72, v73
	v_cvt_pk_bf16_f32 v72, v76, v77
	v_cvt_pk_bf16_f32 v73, v78, v79
	v_cvt_pk_bf16_f32 v74, v74, v75
	v_cvt_pk_bf16_f32 v75, v82, v83
	v_pk_add_f32 v[82:83], v[64:65], v[94:95]
	v_mul_f32_e32 v64, v69, v69
	v_mul_f32_e32 v65, v71, v71
	v_pk_add_f32 v[78:79], v[66:67], v[96:97]
	v_fmac_f32_e32 v64, v68, v68
	v_fmac_f32_e32 v65, v70, v70
	v_add_f32_e32 v64, v64, v65
	v_mul_f32_e32 v65, v83, v83
	v_mul_f32_e32 v66, v79, v79
	v_fmac_f32_e32 v65, v82, v82
	v_fmac_f32_e32 v66, v78, v78
	v_add_f32_e32 v65, v65, v66
	v_add_f32_e32 v64, v64, v65
	v_add_f32_e32 v67, v84, v64
	ds_bpermute_b32 v84, v114, v67
	v_or_b32_e32 v80, 48, v172
	s_waitcnt lgkmcnt(1)
	v_ashrrev_i32_e32 v81, 31, v80
	v_lshlrev_b64 v[76:77], 13, v[80:81]
	v_lshl_add_u64 v[64:65], s[10:11], 0, v[76:77]
	v_lshl_add_u64 v[76:77], v[170:171], 1, v[64:65]
	s_waitcnt lgkmcnt(0)
	v_add_f32_e32 v64, v67, v84
	ds_bpermute_b32 v65, v115, v64
	global_store_dwordx4 v[76:77], v[72:75], off
	v_cvt_pk_bf16_f32 v66, v68, v69
	v_cvt_pk_bf16_f32 v67, v70, v71
	v_cvt_pk_bf16_f32 v68, v82, v83
	v_cvt_pk_bf16_f32 v69, v78, v79
	global_store_dwordx4 v[76:77], v[66:69], off offset:256
	s_and_saveexec_b64 s[28:29], s[2:3]
	s_cbranch_execz .LBB0_1636
	v_lshlrev_b64 v[66:67], 8, v[80:81]
	v_lshl_add_u64 v[66:67], s[12:13], 0, v[66:67]
	v_lshl_add_u64 v[66:67], s[22:23], 2, v[66:67]
	s_lshl_b32 s0, s42, 2
	v_lshl_add_u64 v[66:67], v[66:67], 0, s[0:1]
	s_waitcnt lgkmcnt(0)
	v_add_f32_e32 v64, v64, v65
	global_store_dword v[66:67], v64, off
